# prep: the two half-workgroup jobs run three barriers apart (half 1 enters three barriers early, half 0 leaves three late), on top of the DPP cumsum so no single-wave chain pairs with the other half's
# baseline (speedup 1.0000x reference)
.LBB0_564:
	s_andn2_b64 vcc, exec, s[2:3]
	s_cbranch_vccnz .LBB0_687
	s_cmp_lt_i32 s57, 1
	s_mov_b64 s[2:3], -1
	s_cbranch_scc1 .LBB0_678
	s_cmp_gt_i32 s57, 1
	s_cbranch_scc0 .LBB0_664
	v_readfirstlane_b32 s100, v158
	s_lshr_b32 s100, s100, 8
	s_cmp_eq_u32 s100, 1
	s_cbranch_scc0 .Lpoff_a
	s_barrier
	s_barrier
	s_barrier

.LBB0_663:
	v_readfirstlane_b32 s100, v158
	s_lshr_b32 s100, s100, 8
	s_cmp_eq_u32 s100, 0
	s_cbranch_scc0 .Lpoff_b
	s_barrier
	s_barrier
	s_barrier
